# v32: on top of v31, the next task's gate matmuls (barrier + fragment reads + 8 MFMAs + Gt writes) also moved into the post-publish window; loop top keeps one barrier before the scan
# baseline (speedup 1.0000x reference)
.LBB0_307:
	s_and_b32 s41, s40, 7
	s_cmp_eq_u32 s41, s2
	s_cbranch_scc1 .LBB0_309
	s_lshl_b32 s0, s41, 6
	v_or_b32_e32 v18, s0, v121
	s_mov_b64 s[42:43], s[52:53]
	v_readlane_b32 s52, v254, 60
	v_lshlrev_b32_e32 v38, 2, v18
	v_mov_b32_e32 v39, v196
	v_readlane_b32 s64, v255, 8
	v_readlane_b32 s65, v255, 9
	v_readlane_b32 s53, v254, 61
	v_readlane_b32 s54, v254, 62
	v_readlane_b32 s55, v254, 63
	v_readlane_b32 s56, v255, 0
	v_readlane_b32 s57, v255, 1
	v_readlane_b32 s58, v255, 2
	v_readlane_b32 s59, v255, 3
	v_readlane_b32 s60, v255, 4
	v_readlane_b32 s61, v255, 5
	v_readlane_b32 s62, v255, 6
	v_readlane_b32 s63, v255, 7
	v_readlane_b32 s66, v255, 10
	v_readlane_b32 s67, v255, 11
	v_lshl_add_u64 v[50:51], s[64:65], 0, v[38:39]
	s_mov_b64 s[16:17], 0x1000
	s_movk_i32 s1, 0x1000
	s_nop 1
	global_load_dwordx4 v[22:25], v38, s[66:67] offset:16
	global_load_dwordx4 v[18:21], v38, s[64:65] offset:16
	global_load_dwordx4 v[30:33], v38, s[66:67]
	global_load_dwordx4 v[26:29], v38, s[64:65]
	global_load_dwordx4 v[34:37], v38, s[64:65] offset:2064
	s_nop 0
	global_load_dwordx4 v[38:41], v38, s[64:65] offset:2048
	v_lshl_add_u64 v[42:43], v[50:51], 0, s[16:17]
	v_add_co_u32_e32 v52, vcc, s1, v50
	s_mov_b64 s[16:17], 0x1800
	v_or_b32_e32 v58, s0, v120
	v_readlane_b32 s52, v255, 12
	v_readlane_b32 s0, v255, 43
	v_addc_co_u32_e32 v53, vcc, 0, v51, vcc
	v_lshl_add_u64 v[50:51], v[50:51], 0, s[16:17]
	v_lshlrev_b32_e32 v58, 2, v58
	v_readlane_b32 s54, v255, 14
	v_readlane_b32 s55, v255, 15
	v_readlane_b32 s1, v255, 44
	global_load_dwordx4 v[46:49], v[52:53], off
	s_nop 0
	global_load_dwordx4 v[42:45], v[42:43], off offset:16
	s_nop 0
	global_load_dwordx4 v[54:57], v[52:53], off offset:2048
	s_nop 0
	global_load_dwordx4 v[50:53], v[50:51], off offset:16
	v_readlane_b32 s58, v255, 18
	v_readlane_b32 s59, v255, 19
	global_load_dword v153, v58, s[54:55]
	s_nop 3
	global_load_dword v154, v58, s[58:59]
	global_load_dword v155, v58, s[0:1]
	s_lshl_b32 s0, s41, 13
	s_mov_b32 s1, s46
	v_lshl_add_u64 v[74:75], v[96:97], 0, s[0:1]
	global_load_dwordx4 v[70:73], v[74:75], off
	global_load_dwordx4 v[66:69], v[74:75], off offset:64
	global_load_dwordx4 v[62:65], v[74:75], off offset:2048
	global_load_dwordx4 v[58:61], v[74:75], off offset:2112
	v_add_co_u32_e32 v74, vcc, 0x1000, v74
	v_readlane_b32 s60, v255, 20
	s_nop 0
	v_addc_co_u32_e32 v75, vcc, 0, v75, vcc
	global_load_dwordx4 v[86:89], v[74:75], off
	global_load_dwordx4 v[82:85], v[74:75], off offset:64
	global_load_dwordx4 v[78:81], v[74:75], off offset:2048
	s_nop 0
	global_load_dwordx4 v[74:77], v[74:75], off offset:2112
	v_readlane_b32 s61, v255, 21
	v_readlane_b32 s62, v255, 22
	v_readlane_b32 s63, v255, 23
	v_readlane_b32 s53, v255, 13
	v_readlane_b32 s62, v255, 51
	v_readlane_b32 s60, v255, 49
	s_mov_b64 s[52:53], s[42:43]
	v_readlane_b32 s63, v255, 52
	v_readlane_b32 s61, v255, 50
	s_mov_b32 s2, s41
	v_readlane_b32 s56, v255, 16
	v_readlane_b32 s57, v255, 17
	v_readlane_b32 s64, v255, 24
	v_readlane_b32 s65, v255, 25
	v_readlane_b32 s66, v255, 26
	v_readlane_b32 s67, v255, 27
	s_waitcnt vmcnt(0)
	s_barrier
	v_lshlrev_b32_e32 v98, 16, v6
	v_and_b32_e32 v99, 0xffff0000, v6
	v_pk_fma_f32 v[98:99], v[26:27], v[98:99], v[30:31]
	v_lshlrev_b32_e32 v100, 16, v2
	v_and_b32_e32 v101, 0xffff0000, v2
	v_pk_fma_f32 v[98:99], v[38:39], v[100:101], v[98:99]
	v_lshlrev_b32_e32 v100, 16, v10
	v_and_b32_e32 v101, 0xffff0000, v10
	v_pk_fma_f32 v[98:99], v[46:47], v[100:101], v[98:99]
	v_lshlrev_b32_e32 v100, 16, v14
	v_and_b32_e32 v101, 0xffff0000, v14
	v_pk_fma_f32 v[98:99], v[54:55], v[100:101], v[98:99]
	v_lshlrev_b32_e32 v100, 16, v7
	v_and_b32_e32 v101, 0xffff0000, v7
	v_pk_fma_f32 v[100:101], v[28:29], v[100:101], v[32:33]
	v_lshlrev_b32_e32 v102, 16, v3
	v_and_b32_e32 v103, 0xffff0000, v3
	v_pk_fma_f32 v[100:101], v[40:41], v[102:103], v[100:101]
	v_lshlrev_b32_e32 v102, 16, v11
	v_and_b32_e32 v103, 0xffff0000, v11
	v_pk_fma_f32 v[100:101], v[48:49], v[102:103], v[100:101]
	v_lshlrev_b32_e32 v102, 16, v15
	v_and_b32_e32 v103, 0xffff0000, v15
	v_pk_fma_f32 v[100:101], v[56:57], v[102:103], v[100:101]
	v_lshlrev_b32_e32 v102, 16, v8
	v_and_b32_e32 v103, 0xffff0000, v8
	v_pk_fma_f32 v[102:103], v[18:19], v[102:103], v[22:23]
	v_lshlrev_b32_e32 v104, 16, v4
	v_and_b32_e32 v105, 0xffff0000, v4
	v_pk_fma_f32 v[102:103], v[34:35], v[104:105], v[102:103]
	v_lshlrev_b32_e32 v104, 16, v12
	v_and_b32_e32 v105, 0xffff0000, v12
	v_pk_fma_f32 v[102:103], v[42:43], v[104:105], v[102:103]
	v_lshlrev_b32_e32 v104, 16, v16
	v_and_b32_e32 v105, 0xffff0000, v16
	v_pk_fma_f32 v[102:103], v[50:51], v[104:105], v[102:103]
	v_lshlrev_b32_e32 v104, 16, v9
	v_and_b32_e32 v105, 0xffff0000, v9
	v_pk_fma_f32 v[104:105], v[20:21], v[104:105], v[24:25]
	v_lshlrev_b32_e32 v106, 16, v5
	v_and_b32_e32 v107, 0xffff0000, v5
	v_pk_fma_f32 v[104:105], v[36:37], v[106:107], v[104:105]
	v_lshlrev_b32_e32 v106, 16, v13
	v_and_b32_e32 v107, 0xffff0000, v13
	v_pk_fma_f32 v[104:105], v[44:45], v[106:107], v[104:105]
	v_lshlrev_b32_e32 v106, 16, v17
	v_and_b32_e32 v107, 0xffff0000, v17
	v_pk_fma_f32 v[104:105], v[52:53], v[106:107], v[104:105]
	v_cvt_pk_bf16_f32 v106, v98, v99
	v_cvt_pk_bf16_f32 v107, v100, v101
	v_cvt_pk_bf16_f32 v108, v102, v103
	v_add_u32_e32 v110, v122, v90
	v_cvt_pk_bf16_f32 v109, v104, v105
	ds_write_b128 v110, v[106:109]
	ds_write_b128 v123, v[98:101] offset:9216
	ds_write_b128 v123, v[102:105] offset:9232
	s_waitcnt lgkmcnt(0)
	s_barrier
	ds_read_b128 v[114:117], v147
	ds_read_b128 v[164:167], v147 offset:64
	s_waitcnt lgkmcnt(1)
	v_mfma_f32_16x16x32_bf16 v[168:171], v[114:117], v[70:73], 0
	v_add_u32_e32 v113, 0x6400, v148
	v_mfma_f32_16x16x32_bf16 v[172:175], v[114:117], v[62:65], 0
	s_waitcnt lgkmcnt(0)
	v_mfma_f32_16x16x32_bf16 v[168:171], v[164:167], v[66:69], v[168:171]
	v_mfma_f32_16x16x32_bf16 v[172:175], v[164:167], v[58:61], v[172:175]
	s_nop 7
	ds_write2_b32 v113, v168, v172 offset1:16
	ds_write2_b32 v113, v169, v173 offset0:64 offset1:80
	ds_write2_b32 v113, v170, v174 offset0:128 offset1:144
	ds_write2_b32 v113, v171, v175 offset0:192 offset1:208
	v_mfma_f32_16x16x32_bf16 v[168:171], v[114:117], v[86:89], 0
	v_mfma_f32_16x16x32_bf16 v[114:117], v[114:117], v[78:81], 0
	v_mfma_f32_16x16x32_bf16 v[168:171], v[164:167], v[82:85], v[168:171]
	v_mfma_f32_16x16x32_bf16 v[114:117], v[164:167], v[74:77], v[114:117]
	s_nop 7
	ds_write2_b32 v113, v168, v114 offset0:32 offset1:48
	ds_write2_b32 v113, v169, v115 offset0:96 offset1:112
	ds_write2_b32 v113, v170, v116 offset0:160 offset1:176
	ds_write2_b32 v113, v171, v117 offset0:224 offset1:240

.LBB0_327:
	s_or_b64 exec, exec, s[0:1]
	v_mov_b32_e32 v178, 1.0
	s_waitcnt lgkmcnt(0)
	s_barrier
	ds_read2st64_b32 v[198:199], v129 offset0:36 offset1:100
	ds_read2st64_b32 v[200:201], v131 offset0:36 offset1:100
	ds_read2st64_b32 v[202:203], v133 offset0:36 offset1:100
	ds_read2st64_b32 v[204:205], v135 offset0:36 offset1:100
	ds_read2st64_b32 v[206:207], v137 offset0:36 offset1:100
	ds_read2st64_b32 v[208:209], v139 offset0:36 offset1:100
	ds_read2st64_b32 v[210:211], v141 offset0:36 offset1:100
	ds_read2st64_b32 v[212:213], v143 offset0:36 offset1:100
	ds_read_b32 v214, v130 offset:41984
	ds_read_b32 v215, v132 offset:41984
	ds_read_b32 v216, v134 offset:41984
	ds_read_b32 v217, v136 offset:41984
	ds_read_b32 v218, v138 offset:41984
	ds_read_b32 v219, v140 offset:41984
	ds_read_b32 v220, v142 offset:41984
	ds_read_b32 v221, v144 offset:41984
	s_waitcnt lgkmcnt(8)
	v_add_f32_e32 v199, v153, v199
	v_add_f32_e32 v201, v153, v201
	v_add_f32_e32 v203, v153, v203
	v_add_f32_e32 v205, v153, v205
	v_add_f32_e32 v207, v153, v207
	v_add_f32_e32 v209, v153, v209
	v_add_f32_e32 v211, v153, v211
	v_add_f32_e32 v213, v153, v213
	v_mul_f32_e32 v199, 0xbfb8aa3b, v199
	v_mul_f32_e32 v201, 0xbfb8aa3b, v201
	v_mul_f32_e32 v203, 0xbfb8aa3b, v203
	v_mul_f32_e32 v205, 0xbfb8aa3b, v205
	v_mul_f32_e32 v207, 0xbfb8aa3b, v207
	v_mul_f32_e32 v209, 0xbfb8aa3b, v209
	v_mul_f32_e32 v211, 0xbfb8aa3b, v211
	v_mul_f32_e32 v213, 0xbfb8aa3b, v213
	v_exp_f32_e32 v199, v199
	v_exp_f32_e32 v201, v201
	v_exp_f32_e32 v203, v203
	v_exp_f32_e32 v205, v205
	v_exp_f32_e32 v207, v207
	v_exp_f32_e32 v209, v209
	v_exp_f32_e32 v211, v211
	v_exp_f32_e32 v213, v213
	s_waitcnt lgkmcnt(0)
	v_add_f32_e32 v214, v154, v214
	v_add_f32_e32 v215, v154, v215
	v_add_f32_e32 v216, v154, v216
	v_add_f32_e32 v217, v154, v217
	v_add_f32_e32 v218, v154, v218
	v_add_f32_e32 v219, v154, v219
	v_add_f32_e32 v220, v154, v220
	v_add_f32_e32 v221, v154, v221
	v_add_f32_e32 v199, 1.0, v199
	v_add_f32_e32 v201, 1.0, v201
	v_add_f32_e32 v203, 1.0, v203
	v_add_f32_e32 v205, 1.0, v205
	v_add_f32_e32 v207, 1.0, v207
	v_add_f32_e32 v209, 1.0, v209
	v_add_f32_e32 v211, 1.0, v211
	v_add_f32_e32 v213, 1.0, v213
	v_rcp_f32_e32 v199, v199
	v_rcp_f32_e32 v201, v201
	v_rcp_f32_e32 v203, v203
	v_rcp_f32_e32 v205, v205
	v_rcp_f32_e32 v207, v207
	v_rcp_f32_e32 v209, v209
	v_rcp_f32_e32 v211, v211
	v_rcp_f32_e32 v213, v213
	v_mul_f32_e32 v214, 0xbfb8aa3b, v214
	v_mul_f32_e32 v215, 0xbfb8aa3b, v215
	v_mul_f32_e32 v216, 0xbfb8aa3b, v216
	v_mul_f32_e32 v217, 0xbfb8aa3b, v217
	v_mul_f32_e32 v218, 0xbfb8aa3b, v218
	v_mul_f32_e32 v219, 0xbfb8aa3b, v219
	v_mul_f32_e32 v220, 0xbfb8aa3b, v220
	v_mul_f32_e32 v221, 0xbfb8aa3b, v221
	v_exp_f32_e32 v214, v214
	v_exp_f32_e32 v215, v215
	v_exp_f32_e32 v216, v216
	v_exp_f32_e32 v217, v217
	v_exp_f32_e32 v218, v218
	v_exp_f32_e32 v219, v219
	v_exp_f32_e32 v220, v220
	v_exp_f32_e32 v221, v221
	v_mul_f32_e32 v199, 0x41000000, v199
	v_mul_f32_e32 v201, 0x41000000, v201
	v_mul_f32_e32 v203, 0x41000000, v203
	v_mul_f32_e32 v205, 0x41000000, v205
	v_mul_f32_e32 v207, 0x41000000, v207
	v_mul_f32_e32 v209, 0x41000000, v209
	v_mul_f32_e32 v211, 0x41000000, v211
	v_mul_f32_e32 v213, 0x41000000, v213
	v_mul_f32_e32 v199, v155, v199
	v_mul_f32_e32 v201, v155, v201
	v_mul_f32_e32 v203, v155, v203
	v_mul_f32_e32 v205, v155, v205
	v_mul_f32_e32 v207, v155, v207
	v_mul_f32_e32 v209, v155, v209
	v_mul_f32_e32 v211, v155, v211
	v_mul_f32_e32 v213, v155, v213
	v_mul_f32_e32 v199, 0x3fb8aa3b, v199
	v_mul_f32_e32 v201, 0x3fb8aa3b, v201
	v_mul_f32_e32 v203, 0x3fb8aa3b, v203
	v_mul_f32_e32 v205, 0x3fb8aa3b, v205
	v_mul_f32_e32 v207, 0x3fb8aa3b, v207
	v_mul_f32_e32 v209, 0x3fb8aa3b, v209
	v_mul_f32_e32 v211, 0x3fb8aa3b, v211
	v_mul_f32_e32 v213, 0x3fb8aa3b, v213
	v_exp_f32_e32 v163, v199
	v_exp_f32_e32 v201, v201
	v_exp_f32_e32 v203, v203
	v_exp_f32_e32 v205, v205
	v_exp_f32_e32 v207, v207
	v_exp_f32_e32 v209, v209
	v_exp_f32_e32 v211, v211
	v_exp_f32_e32 v213, v213
	v_add_f32_e32 v214, 1.0, v214
	v_add_f32_e32 v215, 1.0, v215
	v_add_f32_e32 v216, 1.0, v216
	v_add_f32_e32 v217, 1.0, v217
	v_add_f32_e32 v218, 1.0, v218
	v_add_f32_e32 v219, 1.0, v219
	v_add_f32_e32 v220, 1.0, v220
	v_add_f32_e32 v221, 1.0, v221
	v_rcp_f32_e32 v214, v214
	v_rcp_f32_e32 v215, v215
	v_rcp_f32_e32 v216, v216
	v_rcp_f32_e32 v217, v217
	v_rcp_f32_e32 v218, v218
	v_rcp_f32_e32 v219, v219
	v_rcp_f32_e32 v220, v220
	v_rcp_f32_e32 v221, v221
	v_fma_f32 v180, -v163, v163, 1.0
	v_fma_f32 v181, -v201, v201, 1.0
	v_fma_f32 v182, -v203, v203, 1.0
	v_fma_f32 v183, -v205, v205, 1.0
	v_fma_f32 v184, -v207, v207, 1.0
	v_fma_f32 v185, -v209, v209, 1.0
	v_fma_f32 v186, -v211, v211, 1.0
	v_fma_f32 v187, -v213, v213, 1.0
	v_max_f32_e32 v180, 0, v180
	v_max_f32_e32 v181, 0, v181
	v_max_f32_e32 v182, 0, v182
	v_max_f32_e32 v183, 0, v183
	v_max_f32_e32 v184, 0, v184
	v_max_f32_e32 v185, 0, v185
	v_max_f32_e32 v186, 0, v186
	v_max_f32_e32 v187, 0, v187
	v_sqrt_f32_e32 v180, v180
	v_sqrt_f32_e32 v181, v181
	v_sqrt_f32_e32 v182, v182
	v_sqrt_f32_e32 v183, v183
	v_sqrt_f32_e32 v184, v184
	v_sqrt_f32_e32 v185, v185
	v_sqrt_f32_e32 v186, v186
	v_sqrt_f32_e32 v187, v187
	v_mul_f32_e32 v198, v198, v214
	v_mul_f32_e32 v200, v200, v215
	v_mul_f32_e32 v202, v202, v216
	v_mul_f32_e32 v204, v204, v217
	v_mul_f32_e32 v206, v206, v218
	v_mul_f32_e32 v208, v208, v219
	v_mul_f32_e32 v210, v210, v220
	v_mul_f32_e32 v212, v212, v221
	v_mul_f32_e32 v116, 0, v163
	v_fma_f32 v164, v198, v180, v116
	v_mul_f32_e32 v165, v200, v181
	v_mul_f32_e32 v166, v163, v201
	v_fmac_f32_e32 v165, v201, v164
	v_mul_f32_e32 v167, v202, v182
	v_mul_f32_e32 v169, v166, v203
	v_fmac_f32_e32 v167, v203, v165
	v_mul_f32_e32 v168, v204, v183
	v_mul_f32_e32 v171, v169, v205
	v_fmac_f32_e32 v168, v205, v167
	v_mul_f32_e32 v170, v206, v184
	v_mul_f32_e32 v173, v171, v207
	v_fmac_f32_e32 v170, v207, v168
	v_mul_f32_e32 v172, v208, v185
	v_mul_f32_e32 v175, v173, v209
	v_fmac_f32_e32 v172, v209, v170
	v_mul_f32_e32 v174, v210, v186
	v_mul_f32_e32 v176, v175, v211
	v_fmac_f32_e32 v174, v211, v172
	v_mul_f32_e32 v115, v212, v187
	v_mul_f32_e32 v114, v176, v213
	v_fmac_f32_e32 v115, v213, v174
	v_mov_b32_e32 v117, 0
	ds_write_b64 v149, v[114:115] offset:58368
	s_waitcnt lgkmcnt(0)
	s_barrier
	v_readfirstlane_b32 s68, v119
	ds_read_b64 v[226:227], v145
	ds_read_b64 v[228:229], v145 offset:512
	ds_read_b64 v[230:231], v145 offset:1024
	ds_read_b64 v[232:233], v145 offset:1536
	ds_read_b64 v[234:235], v145 offset:2048
	ds_read_b64 v[236:237], v145 offset:2560
	ds_read_b64 v[238:239], v145 offset:3072
	s_waitcnt lgkmcnt(0)
	s_cmp_lt_i32 s68, 1
	s_cbranch_scc1 .Lrnn_pfx_done
	v_mul_f32_e32 v178, v178, v226
	v_fma_f32 v117, v117, v226, v227
	s_cmp_lt_i32 s68, 2
	s_cbranch_scc1 .Lrnn_pfx_done
	v_mul_f32_e32 v178, v178, v228
	v_fma_f32 v117, v117, v228, v229
	s_cmp_lt_i32 s68, 3
	s_cbranch_scc1 .Lrnn_pfx_done
	v_mul_f32_e32 v178, v178, v230
	v_fma_f32 v117, v117, v230, v231
	s_cmp_lt_i32 s68, 4
	s_cbranch_scc1 .Lrnn_pfx_done
	v_mul_f32_e32 v178, v178, v232
	v_fma_f32 v117, v117, v232, v233
	s_cmp_lt_i32 s68, 5
	s_cbranch_scc1 .Lrnn_pfx_done
	v_mul_f32_e32 v178, v178, v234
	v_fma_f32 v117, v117, v234, v235
	s_cmp_lt_i32 s68, 6
	s_cbranch_scc1 .Lrnn_pfx_done
	v_mul_f32_e32 v178, v178, v236
	v_fma_f32 v117, v117, v236, v237
	s_cmp_lt_i32 s68, 7
	s_cbranch_scc1 .Lrnn_pfx_done
	v_mul_f32_e32 v178, v178, v238
	v_fma_f32 v117, v117, v238, v239

.LBB0_331:
	v_fmac_f32_e32 v115, v114, v117
	v_mul_f32_e32 v177, v114, v178
	s_and_saveexec_b64 s[0:1], s[52:53]
	s_cbranch_execz .LBB0_340
	s_add_i32 s68, s73, s33
	s_ashr_i32 s69, s68, 31
	s_lshl_b64 s[68:69], s[68:69], 12
	s_add_u32 s68, s36, s68
	v_or_b32_e32 v114, 1, v177
	s_addc_u32 s69, s37, s69
	global_store_dwordx2 v112, v[114:115], s[68:69] sc1
	s_or_b64 exec, exec, s[0:1]
	s_waitcnt vmcnt(1)
	v_lshlrev_b32_e32 v179, 16, v101
	v_mul_f32_e32 v222, 0x3d372713, v179
	v_mul_f32_e32 v222, v222, v179
	v_fma_f32 v222, v222, v179, v179
	v_mul_f32_e32 v222, 0x3f4c422a, v222
	v_add_f32_e32 v222, v222, v222
	v_mul_f32_e32 v222, 0x3fb8aa3b, v222
	v_exp_f32_e32 v222, v222
	v_mul_f32_e32 v179, 0.5, v179
	v_add_f32_e32 v222, 1.0, v222
	v_rcp_f32_e32 v222, v222
	s_nop 0
	v_fma_f32 v222, v222, -2.0, 1.0
	v_add_f32_e32 v222, 1.0, v222
	v_mul_f32_e32 v188, v179, v222
	v_lshlrev_b32_e32 v179, 16, v162
	v_mul_f32_e32 v222, 0x3d372713, v179
	v_mul_f32_e32 v222, v222, v179
	v_fma_f32 v222, v222, v179, v179
	v_mul_f32_e32 v222, 0x3f4c422a, v222
	v_add_f32_e32 v222, v222, v222
	v_mul_f32_e32 v222, 0x3fb8aa3b, v222
	v_exp_f32_e32 v222, v222
	v_mul_f32_e32 v179, 0.5, v179
	v_add_f32_e32 v222, 1.0, v222
	v_rcp_f32_e32 v222, v222
	s_nop 0
	v_fma_f32 v222, v222, -2.0, 1.0
	v_add_f32_e32 v222, 1.0, v222
	v_mul_f32_e32 v189, v179, v222
	v_lshlrev_b32_e32 v179, 16, v161
	v_mul_f32_e32 v222, 0x3d372713, v179
	v_mul_f32_e32 v222, v222, v179
	v_fma_f32 v222, v222, v179, v179
	v_mul_f32_e32 v222, 0x3f4c422a, v222
	v_add_f32_e32 v222, v222, v222
	v_mul_f32_e32 v222, 0x3fb8aa3b, v222
	v_exp_f32_e32 v222, v222
	v_mul_f32_e32 v179, 0.5, v179
	v_add_f32_e32 v222, 1.0, v222
	v_rcp_f32_e32 v222, v222
	s_nop 0
	v_fma_f32 v222, v222, -2.0, 1.0
	v_add_f32_e32 v222, 1.0, v222
	v_mul_f32_e32 v190, v179, v222
	v_lshlrev_b32_e32 v179, 16, v160
	v_mul_f32_e32 v222, 0x3d372713, v179
	v_mul_f32_e32 v222, v222, v179
	v_fma_f32 v222, v222, v179, v179
	v_mul_f32_e32 v222, 0x3f4c422a, v222
	v_add_f32_e32 v222, v222, v222
	v_mul_f32_e32 v222, 0x3fb8aa3b, v222
	v_exp_f32_e32 v222, v222
	v_mul_f32_e32 v179, 0.5, v179
	v_add_f32_e32 v222, 1.0, v222
	v_rcp_f32_e32 v222, v222
	s_nop 0
	v_fma_f32 v222, v222, -2.0, 1.0
	v_add_f32_e32 v222, 1.0, v222
	v_mul_f32_e32 v191, v179, v222
	v_lshlrev_b32_e32 v179, 16, v159
	v_mul_f32_e32 v222, 0x3d372713, v179
	v_mul_f32_e32 v222, v222, v179
	v_fma_f32 v222, v222, v179, v179
	v_mul_f32_e32 v222, 0x3f4c422a, v222
	v_add_f32_e32 v222, v222, v222
	v_mul_f32_e32 v222, 0x3fb8aa3b, v222
	v_exp_f32_e32 v222, v222
	v_mul_f32_e32 v179, 0.5, v179
	v_add_f32_e32 v222, 1.0, v222
	v_rcp_f32_e32 v222, v222
	s_nop 0
	v_fma_f32 v222, v222, -2.0, 1.0
	v_add_f32_e32 v222, 1.0, v222
	v_mul_f32_e32 v192, v179, v222
	v_lshlrev_b32_e32 v179, 16, v158
	v_mul_f32_e32 v222, 0x3d372713, v179
	v_mul_f32_e32 v222, v222, v179
	v_fma_f32 v222, v222, v179, v179
	v_mul_f32_e32 v222, 0x3f4c422a, v222
	v_add_f32_e32 v222, v222, v222
	v_mul_f32_e32 v222, 0x3fb8aa3b, v222
	v_exp_f32_e32 v222, v222
	v_mul_f32_e32 v179, 0.5, v179
	v_add_f32_e32 v222, 1.0, v222
	v_rcp_f32_e32 v222, v222
	s_nop 0
	v_fma_f32 v222, v222, -2.0, 1.0
	v_add_f32_e32 v222, 1.0, v222
	v_mul_f32_e32 v193, v179, v222
	v_lshlrev_b32_e32 v179, 16, v157
	v_mul_f32_e32 v222, 0x3d372713, v179
	v_mul_f32_e32 v222, v222, v179
	v_fma_f32 v222, v222, v179, v179
	v_mul_f32_e32 v222, 0x3f4c422a, v222
	v_add_f32_e32 v222, v222, v222
	v_mul_f32_e32 v222, 0x3fb8aa3b, v222
	v_exp_f32_e32 v222, v222
	v_mul_f32_e32 v179, 0.5, v179
	v_add_f32_e32 v222, 1.0, v222
	v_rcp_f32_e32 v222, v222
	s_nop 0
	v_fma_f32 v222, v222, -2.0, 1.0
	v_add_f32_e32 v222, 1.0, v222
	v_mul_f32_e32 v194, v179, v222
	v_lshlrev_b32_e32 v179, 16, v156
	v_mul_f32_e32 v222, 0x3d372713, v179
	v_mul_f32_e32 v222, v222, v179
	v_fma_f32 v222, v222, v179, v179
	v_mul_f32_e32 v222, 0x3f4c422a, v222
	v_add_f32_e32 v222, v222, v222
	v_mul_f32_e32 v222, 0x3fb8aa3b, v222
	v_exp_f32_e32 v222, v222
	v_mul_f32_e32 v179, 0.5, v179
	v_add_f32_e32 v222, 1.0, v222
	v_rcp_f32_e32 v222, v222
	s_nop 0
	v_fma_f32 v222, v222, -2.0, 1.0
	v_add_f32_e32 v222, 1.0, v222
	v_mul_f32_e32 v195, v179, v222
	v_lshlrev_b32_e32 v226, 16, v6
	v_and_b32_e32 v227, 0xffff0000, v6
	v_pk_fma_f32 v[226:227], v[26:27], v[226:227], v[30:31]
	v_lshlrev_b32_e32 v228, 16, v2
	v_and_b32_e32 v229, 0xffff0000, v2
	v_pk_fma_f32 v[226:227], v[38:39], v[228:229], v[226:227]
	v_lshlrev_b32_e32 v228, 16, v10
	v_and_b32_e32 v229, 0xffff0000, v10
	v_pk_fma_f32 v[226:227], v[46:47], v[228:229], v[226:227]
	v_lshlrev_b32_e32 v228, 16, v14
	v_and_b32_e32 v229, 0xffff0000, v14
	v_pk_fma_f32 v[226:227], v[54:55], v[228:229], v[226:227]
	v_lshlrev_b32_e32 v228, 16, v7
	v_and_b32_e32 v229, 0xffff0000, v7
	v_pk_fma_f32 v[228:229], v[28:29], v[228:229], v[32:33]
	v_lshlrev_b32_e32 v230, 16, v3
	v_and_b32_e32 v231, 0xffff0000, v3
	v_pk_fma_f32 v[228:229], v[40:41], v[230:231], v[228:229]
	v_lshlrev_b32_e32 v230, 16, v11
	v_and_b32_e32 v231, 0xffff0000, v11
	v_pk_fma_f32 v[228:229], v[48:49], v[230:231], v[228:229]
	v_lshlrev_b32_e32 v230, 16, v15
	v_and_b32_e32 v231, 0xffff0000, v15
	v_pk_fma_f32 v[228:229], v[56:57], v[230:231], v[228:229]
	v_lshlrev_b32_e32 v230, 16, v8
	v_and_b32_e32 v231, 0xffff0000, v8
	v_pk_fma_f32 v[230:231], v[18:19], v[230:231], v[22:23]
	v_lshlrev_b32_e32 v232, 16, v4
	v_and_b32_e32 v233, 0xffff0000, v4
	v_pk_fma_f32 v[230:231], v[34:35], v[232:233], v[230:231]
	v_lshlrev_b32_e32 v232, 16, v12
	v_and_b32_e32 v233, 0xffff0000, v12
	v_pk_fma_f32 v[230:231], v[42:43], v[232:233], v[230:231]
	v_lshlrev_b32_e32 v232, 16, v16
	v_and_b32_e32 v233, 0xffff0000, v16
	v_pk_fma_f32 v[230:231], v[50:51], v[232:233], v[230:231]
	v_lshlrev_b32_e32 v232, 16, v9
	v_and_b32_e32 v233, 0xffff0000, v9
	v_pk_fma_f32 v[232:233], v[20:21], v[232:233], v[24:25]
	v_lshlrev_b32_e32 v234, 16, v5
	v_and_b32_e32 v235, 0xffff0000, v5
	v_pk_fma_f32 v[232:233], v[36:37], v[234:235], v[232:233]
	v_lshlrev_b32_e32 v234, 16, v13
	v_and_b32_e32 v235, 0xffff0000, v13
	v_pk_fma_f32 v[232:233], v[44:45], v[234:235], v[232:233]
	v_lshlrev_b32_e32 v234, 16, v17
	v_and_b32_e32 v235, 0xffff0000, v17
	v_pk_fma_f32 v[232:233], v[52:53], v[234:235], v[232:233]
	v_cvt_pk_bf16_f32 v234, v226, v227
	v_cvt_pk_bf16_f32 v235, v228, v229
	v_cvt_pk_bf16_f32 v236, v230, v231
	v_add_u32_e32 v238, v122, v90
	v_cvt_pk_bf16_f32 v237, v232, v233
	ds_write_b128 v238, v[234:237]
	ds_write_b128 v123, v[226:229] offset:9216
	ds_write_b128 v123, v[230:233] offset:9232
	s_waitcnt lgkmcnt(0)
	s_barrier
	ds_read_b128 v[226:229], v147
	ds_read_b128 v[230:233], v147 offset:64
	s_waitcnt lgkmcnt(1)
	v_mfma_f32_16x16x32_bf16 v[234:237], v[226:229], v[70:73], 0
	v_add_u32_e32 v242, 0x6400, v148
	v_mfma_f32_16x16x32_bf16 v[238:241], v[226:229], v[62:65], 0
	s_waitcnt lgkmcnt(0)
	v_mfma_f32_16x16x32_bf16 v[234:237], v[230:233], v[66:69], v[234:237]
	v_mfma_f32_16x16x32_bf16 v[238:241], v[230:233], v[58:61], v[238:241]
	s_nop 7
	ds_write2_b32 v242, v234, v238 offset1:16
	ds_write2_b32 v242, v235, v239 offset0:64 offset1:80
	ds_write2_b32 v242, v236, v240 offset0:128 offset1:144
	ds_write2_b32 v242, v237, v241 offset0:192 offset1:208
	v_mfma_f32_16x16x32_bf16 v[234:237], v[226:229], v[86:89], 0
	v_mfma_f32_16x16x32_bf16 v[226:229], v[226:229], v[78:81], 0
	v_mfma_f32_16x16x32_bf16 v[234:237], v[230:233], v[82:85], v[234:237]
	v_mfma_f32_16x16x32_bf16 v[226:229], v[230:233], v[74:77], v[226:229]
	s_nop 7
	ds_write2_b32 v242, v234, v226 offset0:32 offset1:48
	ds_write2_b32 v242, v235, v227 offset0:96 offset1:112
	ds_write2_b32 v242, v236, v228 offset0:160 offset1:176
	ds_write2_b32 v242, v237, v229 offset0:224 offset1:240
	s_and_saveexec_b64 s[68:69], s[44:45]
	s_cbranch_execnz .LBB0_341

.LBB0_340:
	s_or_b64 exec, exec, s[0:1]
	s_waitcnt vmcnt(0)
	v_lshlrev_b32_e32 v179, 16, v101
	v_mul_f32_e32 v222, 0x3d372713, v179
	v_mul_f32_e32 v222, v222, v179
	v_fma_f32 v222, v222, v179, v179
	v_mul_f32_e32 v222, 0x3f4c422a, v222
	v_add_f32_e32 v222, v222, v222
	v_mul_f32_e32 v222, 0x3fb8aa3b, v222
	v_exp_f32_e32 v222, v222
	v_mul_f32_e32 v179, 0.5, v179
	v_add_f32_e32 v222, 1.0, v222
	v_rcp_f32_e32 v222, v222
	s_nop 0
	v_fma_f32 v222, v222, -2.0, 1.0
	v_add_f32_e32 v222, 1.0, v222
	v_mul_f32_e32 v188, v179, v222
	v_lshlrev_b32_e32 v179, 16, v162
	v_mul_f32_e32 v222, 0x3d372713, v179
	v_mul_f32_e32 v222, v222, v179
	v_fma_f32 v222, v222, v179, v179
	v_mul_f32_e32 v222, 0x3f4c422a, v222
	v_add_f32_e32 v222, v222, v222
	v_mul_f32_e32 v222, 0x3fb8aa3b, v222
	v_exp_f32_e32 v222, v222
	v_mul_f32_e32 v179, 0.5, v179
	v_add_f32_e32 v222, 1.0, v222
	v_rcp_f32_e32 v222, v222
	s_nop 0
	v_fma_f32 v222, v222, -2.0, 1.0
	v_add_f32_e32 v222, 1.0, v222
	v_mul_f32_e32 v189, v179, v222
	v_lshlrev_b32_e32 v179, 16, v161
	v_mul_f32_e32 v222, 0x3d372713, v179
	v_mul_f32_e32 v222, v222, v179
	v_fma_f32 v222, v222, v179, v179
	v_mul_f32_e32 v222, 0x3f4c422a, v222
	v_add_f32_e32 v222, v222, v222
	v_mul_f32_e32 v222, 0x3fb8aa3b, v222
	v_exp_f32_e32 v222, v222
	v_mul_f32_e32 v179, 0.5, v179
	v_add_f32_e32 v222, 1.0, v222
	v_rcp_f32_e32 v222, v222
	s_nop 0
	v_fma_f32 v222, v222, -2.0, 1.0
	v_add_f32_e32 v222, 1.0, v222
	v_mul_f32_e32 v190, v179, v222
	v_lshlrev_b32_e32 v179, 16, v160
	v_mul_f32_e32 v222, 0x3d372713, v179
	v_mul_f32_e32 v222, v222, v179
	v_fma_f32 v222, v222, v179, v179
	v_mul_f32_e32 v222, 0x3f4c422a, v222
	v_add_f32_e32 v222, v222, v222
	v_mul_f32_e32 v222, 0x3fb8aa3b, v222
	v_exp_f32_e32 v222, v222
	v_mul_f32_e32 v179, 0.5, v179
	v_add_f32_e32 v222, 1.0, v222
	v_rcp_f32_e32 v222, v222
	s_nop 0
	v_fma_f32 v222, v222, -2.0, 1.0
	v_add_f32_e32 v222, 1.0, v222
	v_mul_f32_e32 v191, v179, v222
	v_lshlrev_b32_e32 v179, 16, v159
	v_mul_f32_e32 v222, 0x3d372713, v179
	v_mul_f32_e32 v222, v222, v179
	v_fma_f32 v222, v222, v179, v179
	v_mul_f32_e32 v222, 0x3f4c422a, v222
	v_add_f32_e32 v222, v222, v222
	v_mul_f32_e32 v222, 0x3fb8aa3b, v222
	v_exp_f32_e32 v222, v222
	v_mul_f32_e32 v179, 0.5, v179
	v_add_f32_e32 v222, 1.0, v222
	v_rcp_f32_e32 v222, v222
	s_nop 0
	v_fma_f32 v222, v222, -2.0, 1.0
	v_add_f32_e32 v222, 1.0, v222
	v_mul_f32_e32 v192, v179, v222
	v_lshlrev_b32_e32 v179, 16, v158
	v_mul_f32_e32 v222, 0x3d372713, v179
	v_mul_f32_e32 v222, v222, v179
	v_fma_f32 v222, v222, v179, v179
	v_mul_f32_e32 v222, 0x3f4c422a, v222
	v_add_f32_e32 v222, v222, v222
	v_mul_f32_e32 v222, 0x3fb8aa3b, v222
	v_exp_f32_e32 v222, v222
	v_mul_f32_e32 v179, 0.5, v179
	v_add_f32_e32 v222, 1.0, v222
	v_rcp_f32_e32 v222, v222
	s_nop 0
	v_fma_f32 v222, v222, -2.0, 1.0
	v_add_f32_e32 v222, 1.0, v222
	v_mul_f32_e32 v193, v179, v222
	v_lshlrev_b32_e32 v179, 16, v157
	v_mul_f32_e32 v222, 0x3d372713, v179
	v_mul_f32_e32 v222, v222, v179
	v_fma_f32 v222, v222, v179, v179
	v_mul_f32_e32 v222, 0x3f4c422a, v222
	v_add_f32_e32 v222, v222, v222
	v_mul_f32_e32 v222, 0x3fb8aa3b, v222
	v_exp_f32_e32 v222, v222
	v_mul_f32_e32 v179, 0.5, v179
	v_add_f32_e32 v222, 1.0, v222
	v_rcp_f32_e32 v222, v222
	s_nop 0
	v_fma_f32 v222, v222, -2.0, 1.0
	v_add_f32_e32 v222, 1.0, v222
	v_mul_f32_e32 v194, v179, v222
	v_lshlrev_b32_e32 v179, 16, v156
	v_mul_f32_e32 v222, 0x3d372713, v179
	v_mul_f32_e32 v222, v222, v179
	v_fma_f32 v222, v222, v179, v179
	v_mul_f32_e32 v222, 0x3f4c422a, v222
	v_add_f32_e32 v222, v222, v222
	v_mul_f32_e32 v222, 0x3fb8aa3b, v222
	v_exp_f32_e32 v222, v222
	v_mul_f32_e32 v179, 0.5, v179
	v_add_f32_e32 v222, 1.0, v222
	v_rcp_f32_e32 v222, v222
	s_nop 0
	v_fma_f32 v222, v222, -2.0, 1.0
	v_add_f32_e32 v222, 1.0, v222
	v_mul_f32_e32 v195, v179, v222
	v_lshlrev_b32_e32 v226, 16, v6
	v_and_b32_e32 v227, 0xffff0000, v6
	v_pk_fma_f32 v[226:227], v[26:27], v[226:227], v[30:31]
	v_lshlrev_b32_e32 v228, 16, v2
	v_and_b32_e32 v229, 0xffff0000, v2
	v_pk_fma_f32 v[226:227], v[38:39], v[228:229], v[226:227]
	v_lshlrev_b32_e32 v228, 16, v10
	v_and_b32_e32 v229, 0xffff0000, v10
	v_pk_fma_f32 v[226:227], v[46:47], v[228:229], v[226:227]
	v_lshlrev_b32_e32 v228, 16, v14
	v_and_b32_e32 v229, 0xffff0000, v14
	v_pk_fma_f32 v[226:227], v[54:55], v[228:229], v[226:227]
	v_lshlrev_b32_e32 v228, 16, v7
	v_and_b32_e32 v229, 0xffff0000, v7
	v_pk_fma_f32 v[228:229], v[28:29], v[228:229], v[32:33]
	v_lshlrev_b32_e32 v230, 16, v3
	v_and_b32_e32 v231, 0xffff0000, v3
	v_pk_fma_f32 v[228:229], v[40:41], v[230:231], v[228:229]
	v_lshlrev_b32_e32 v230, 16, v11
	v_and_b32_e32 v231, 0xffff0000, v11
	v_pk_fma_f32 v[228:229], v[48:49], v[230:231], v[228:229]
	v_lshlrev_b32_e32 v230, 16, v15
	v_and_b32_e32 v231, 0xffff0000, v15
	v_pk_fma_f32 v[228:229], v[56:57], v[230:231], v[228:229]
	v_lshlrev_b32_e32 v230, 16, v8
	v_and_b32_e32 v231, 0xffff0000, v8
	v_pk_fma_f32 v[230:231], v[18:19], v[230:231], v[22:23]
	v_lshlrev_b32_e32 v232, 16, v4
	v_and_b32_e32 v233, 0xffff0000, v4
	v_pk_fma_f32 v[230:231], v[34:35], v[232:233], v[230:231]
	v_lshlrev_b32_e32 v232, 16, v12
	v_and_b32_e32 v233, 0xffff0000, v12
	v_pk_fma_f32 v[230:231], v[42:43], v[232:233], v[230:231]
	v_lshlrev_b32_e32 v232, 16, v16
	v_and_b32_e32 v233, 0xffff0000, v16
	v_pk_fma_f32 v[230:231], v[50:51], v[232:233], v[230:231]
	v_lshlrev_b32_e32 v232, 16, v9
	v_and_b32_e32 v233, 0xffff0000, v9
	v_pk_fma_f32 v[232:233], v[20:21], v[232:233], v[24:25]
	v_lshlrev_b32_e32 v234, 16, v5
	v_and_b32_e32 v235, 0xffff0000, v5
	v_pk_fma_f32 v[232:233], v[36:37], v[234:235], v[232:233]
	v_lshlrev_b32_e32 v234, 16, v13
	v_and_b32_e32 v235, 0xffff0000, v13
	v_pk_fma_f32 v[232:233], v[44:45], v[234:235], v[232:233]
	v_lshlrev_b32_e32 v234, 16, v17
	v_and_b32_e32 v235, 0xffff0000, v17
	v_pk_fma_f32 v[232:233], v[52:53], v[234:235], v[232:233]
	v_cvt_pk_bf16_f32 v234, v226, v227
	v_cvt_pk_bf16_f32 v235, v228, v229
	v_cvt_pk_bf16_f32 v236, v230, v231
	v_add_u32_e32 v238, v122, v90
	v_cvt_pk_bf16_f32 v237, v232, v233
	ds_write_b128 v238, v[234:237]
	ds_write_b128 v123, v[226:229] offset:9216
	ds_write_b128 v123, v[230:233] offset:9232
	s_waitcnt lgkmcnt(0)
	s_barrier
	ds_read_b128 v[226:229], v147
	ds_read_b128 v[230:233], v147 offset:64
	s_waitcnt lgkmcnt(1)
	v_mfma_f32_16x16x32_bf16 v[234:237], v[226:229], v[70:73], 0
	v_add_u32_e32 v242, 0x6400, v148
	v_mfma_f32_16x16x32_bf16 v[238:241], v[226:229], v[62:65], 0
	s_waitcnt lgkmcnt(0)
	v_mfma_f32_16x16x32_bf16 v[234:237], v[230:233], v[66:69], v[234:237]
	v_mfma_f32_16x16x32_bf16 v[238:241], v[230:233], v[58:61], v[238:241]
	s_nop 7
	ds_write2_b32 v242, v234, v238 offset1:16
	ds_write2_b32 v242, v235, v239 offset0:64 offset1:80
	ds_write2_b32 v242, v236, v240 offset0:128 offset1:144
	ds_write2_b32 v242, v237, v241 offset0:192 offset1:208
	v_mfma_f32_16x16x32_bf16 v[234:237], v[226:229], v[86:89], 0
	v_mfma_f32_16x16x32_bf16 v[226:229], v[226:229], v[78:81], 0
	v_mfma_f32_16x16x32_bf16 v[234:237], v[230:233], v[82:85], v[234:237]
	v_mfma_f32_16x16x32_bf16 v[226:229], v[230:233], v[74:77], v[226:229]
	s_nop 7
	ds_write2_b32 v242, v234, v226 offset0:32 offset1:48
	ds_write2_b32 v242, v235, v227 offset0:96 offset1:112
	ds_write2_b32 v242, v236, v228 offset0:160 offset1:176
	ds_write2_b32 v242, v237, v229 offset0:224 offset1:240
	s_and_saveexec_b64 s[68:69], s[44:45]
	s_cbranch_execz .LBB0_333
